# + m20: sync-only grid barriers (no L2 write-back/invalidate) after the W_a/W_b and batch-0 W_out phases, whose exchanged data is produced and consumed on the same XCD; guarded by a run-time check of t
# baseline (speedup 1.0000x reference)
; #define LAS __attribute__((address_space(3)))
; __global__ void __launch_bounds__(512, 2) mega(Args a) {
;     extern __shared__ __attribute__((aligned(16))) unsigned char lds_raw[];
;     LAS unsigned char* lds = (LAS unsigned char*)lds_raw;
;     if (threadIdx.x < 4) ((LAS unsigned*)(lds + LDS_ST))[threadIdx.x] = 0u;
;     __syncthreads();
;     (void)xcd_barrier_post((unsigned*)(a.ws + WS_BAR), (volatile LAS unsigned*)(lds + LDS_ST));
;     int rep = 0;
;     for (int st = a.ph_lo; ; ) {
;         int tid = threadIdx.x; asm volatile("" : "+v"(tid));
;         KArgs ka = (KArgs)__builtin_amdgcn_kernarg_segment_ptr(); asm volatile("" : "+s"(ka));
;         unsigned char* ws = ka->ws; float* X = ka->out;
;         int bid = blockIdx.x; asm volatile("" : "+s"(bid));
;         const int lane = tid & 63, wave = __builtin_amdgcn_readfirstlane(tid >> 6);
;         const int l = st / PH_PER_LAYER, idx = st % PH_PER_LAYER;
;         const float* xin = l == 0 ? ka->in[0] : X;
;         const bool fusedR1 = (gridDim.x == 256);
.LBB0_5:
	s_or_b64 exec, exec, s[4:5]
	s_add_u32 s96, s92, 0xc8
	s_addc_u32 s97, s93, 0
	s_lshl_b32 s0, s91, 9
	v_lshrrev_b32_e32 v1, 20, v0
	v_lshrrev_b32_e32 v0, 10, v0
	v_writelane_b32 v255, s0, 0
	s_mov_b32 s1, 0
	v_writelane_b32 v255, s1, 42
	v_or_b32_e32 v0, v0, v1
	s_movk_i32 s0, 0x3ff
	v_and_or_b32 v0, v0, s0, v222
	s_lshl_b32 s0, s91, 10
	s_lshl_b32 s1, s91, 3
	v_writelane_b32 v255, s0, 1
	v_writelane_b32 v255, s1, 2
	s_add_i32 s0, s1, 0x4000
	v_writelane_b32 v255, s0, 3
	s_lshl_b32 s0, s91, 8
	v_writelane_b32 v255, s0, 4
	s_lshl_b32 s0, s91, 4
	s_add_i32 s1, s0, 0x1b500
	v_writelane_b32 v255, s1, 5
	s_add_i32 s1, s0, 0x1c000
	v_writelane_b32 v255, s1, 6
	s_add_i32 s1, s0, 0x1da00
	v_writelane_b32 v255, s1, 7
	v_writelane_b32 v255, s0, 8
	s_add_i32 s0, s0, 0x1e000
	v_writelane_b32 v255, s0, 9
	s_add_i32 s0, 0, 0x22ff0
	v_writelane_b32 v255, s0, 10
	s_add_i32 s0, 0, 0x22ff4
	v_writelane_b32 v255, s0, 11
	v_cmp_eq_u32_e64 s[0:1], 0, v0
	v_mbcnt_lo_u32_b32 v1, -1, 0
	s_movk_i32 s65, 0x400
	v_writelane_b32 v255, s0, 12
	v_mov_b32_e32 v193, 0
	v_mov_b64_e32 v[208:209], 0x200
	v_mov_b64_e32 v[224:225], 0x1ff
	s_movk_i32 s5, 0x90
	s_mov_b32 s50, 0xffff0000
	s_movk_i32 s51, 0x7fff
	v_mov_b32_e32 v223, 0x358637bd
	s_mov_b32 s24, 0x800000
	s_mov_b32 s25, 0x13a00000
	s_mov_b32 s39, 0xffff
	s_movk_i32 s42, 0x110
	s_movk_i32 s43, 0x48
	s_movk_i32 s61, 0x88
	s_add_i32 s63, 0, 0x1e400
	s_movk_i32 s57, 0x210
	s_mov_b32 s33, 0x5040100
	s_mov_b32 s4, 0x12a00000
	v_mbcnt_hi_u32_b32 v254, -1, v1
	v_mov_b64_e32 v[198:199], 0x100
	v_mov_b64_e32 v[200:201], 0xff
	v_mov_b64_e32 v[228:229], 0xb00
	v_mov_b64_e32 v[250:251], 0xaff
	v_mov_b64_e32 v[252:253], 0x800
	s_mov_b32 s56, 0x18a00000
	v_writelane_b32 v255, s1, 13
	s_mov_b64 s[36:37], 0x80
	s_mov_b64 s[72:73], 0x20000
	s_mov_b64 s[48:49], 0x8000
	s_mov_b64 s[22:23], 0x200000
	s_branch .LBB0_7

; __device__ __forceinline__ void xcd_barrier(const XcdBarrier& b) {
;     asm volatile("s_waitcnt vmcnt(0)" ::: "memory");
;     __syncthreads();
;     if (threadIdx.x == 0) {
;         unsigned* bar = b.bar;
;         __builtin_amdgcn_s_waitcnt(0);
;         unsigned nloc = b.st[0], nx = b.st[1];
;         if (nloc == 0u) { xcd_barrier_complete(bar, b.x, nloc, nx); b.st[0] = nloc; b.st[1] = nx; }
.Lnoskip:
	s_getreg_b32 s1, hwreg(HW_REG_XCC_ID, 0, 4)
	s_waitcnt vmcnt(0)
	s_waitcnt vmcnt(0)
	s_barrier
	s_and_saveexec_b64 s[6:7], s[94:95]
	s_cbranch_execz .LBB0_776
	v_readlane_b32 s2, v255, 10
	s_waitcnt vmcnt(0) expcnt(0) lgkmcnt(0)
	s_and_b32 s1, s1, 15
	s_cmp_lg_u32 s3, 0
	s_cbranch_scc1 .Lpl_1
	v_readlane_b32 s98, v255, 2
	s_nop 3
	s_lshr_b32 s98, s98, 3
	s_cmp_gt_u32 s98, 7
	s_cbranch_scc1 .Lpl_end
	s_lshl_b32 s98, s98, 2
	s_add_i32 s99, s1, 1
	v_mov_b32_e32 v4, s98
	v_mov_b32_e32 v3, s99
	v_add_u32_e32 v4, 0x83800, v4
	global_store_dword v4, v3, s[30:31] sc1
	s_waitcnt vmcnt(0)
	s_branch .Lpl_end
.Lpl_1:
	s_cmp_lg_u32 s3, 1
	s_cbranch_scc1 .Lpl_2
	v_readlane_b32 s98, v255, 2
	s_nop 3
	s_lshr_b32 s98, s98, 3
	s_and_b32 s98, s98, 7
	s_lshl_b32 s98, s98, 2
	v_mov_b32_e32 v4, s98
	v_add_u32_e32 v4, 0x83800, v4
	global_load_dword v3, v4, s[30:31] sc1
	s_add_i32 s99, s1, 1
	s_waitcnt vmcnt(0)
	v_readfirstlane_b32 s98, v3
	s_nop 3
	s_cmp_eq_u32 s98, s99
	s_cbranch_scc1 .Lpl_end
	v_mov_b32_e32 v3, 1
	v_mov_b32_e32 v4, 0x83840
	global_store_dword v4, v3, s[30:31] sc1
	s_waitcnt vmcnt(0)
	s_branch .Lpl_end
.Lpl_2:
	s_cmp_lg_u32 s3, 2
	s_cbranch_scc1 .Lpl_end
	v_mov_b32_e32 v4, 0x83840
	global_load_dword v3, v4, s[30:31] sc1
	s_waitcnt vmcnt(0)
	v_readfirstlane_b32 s98, v3
	s_nop 3
	s_cmp_eq_u32 s98, 0
	s_cselect_b32 s98, 1, 0
	v_writelane_b32 v255, s98, 42
.Lpl_end:
	v_mov_b32_e32 v0, s2
	ds_read_b32 v2, v0
	v_readlane_b32 s2, v255, 11
	s_waitcnt lgkmcnt(0)
	v_cmp_ne_u32_e32 vcc, 0, v2
	v_mov_b32_e32 v0, s2
	ds_read_b32 v0, v0
	s_cbranch_vccnz .LBB0_740
	s_load_dwordx2 s[12:13], s[96:97], 0x4
	s_add_u32 s8, s30, 0x80200
	s_addc_u32 s9, s31, 0
	s_add_u32 s10, s30, 0x80400
	s_addc_u32 s11, s31, 0
	s_waitcnt lgkmcnt(0)
	s_mul_i32 s2, s12, s75
	s_add_u32 s12, s30, 0x80500
	s_mul_i32 s2, s2, s13
	s_addc_u32 s13, s31, 0
	s_add_u32 s14, s30, 0x80600
	s_addc_u32 s15, s31, 0
	s_add_u32 s16, s30, 0x80700
	s_addc_u32 s17, s31, 0
	s_add_u32 s18, s30, 0x80800
	s_addc_u32 s19, s31, 0
	s_add_u32 s20, s30, 0x80900
	s_addc_u32 s21, s31, 0
	s_add_u32 s22, s30, 0x80a00
	s_addc_u32 s23, s31, 0
	s_add_u32 s28, s30, 0x80b00
	s_addc_u32 s29, s31, 0
	s_add_u32 s44, s30, 0x80c00
	s_addc_u32 s45, s31, 0
	s_add_u32 s58, s30, 0x80d00
	s_addc_u32 s59, s31, 0
	s_add_u32 s66, s30, 0x80e00
	s_addc_u32 s67, s31, 0
	s_add_u32 s68, s30, 0x80f00
	s_addc_u32 s69, s31, 0
	s_add_u32 s70, s30, 0x81000
	s_addc_u32 s71, s31, 0
	s_add_u32 s72, s30, 0x81100
	s_addc_u32 s73, s31, 0
	s_add_u32 s74, s30, 0x81200
	s_addc_u32 s75, s31, 0
	s_add_u32 s76, s30, 0x81300
	s_addc_u32 s77, s31, 0
	s_mov_b32 s26, 1
	s_branch .LBB0_728

; __device__ __forceinline__ unsigned xb_ld(unsigned* p)              { return __hip_atomic_load(p, __ATOMIC_RELAXED, __HIP_MEMORY_SCOPE_AGENT); }
; __device__ __forceinline__ unsigned xb_add(unsigned* p, unsigned v) { return __hip_atomic_fetch_add(p, v, __ATOMIC_RELAXED, __HIP_MEMORY_SCOPE_AGENT); }
; #define XB_SPIN(cond, bar) do { unsigned _sp = 0; while (cond) { __builtin_amdgcn_s_sleep(0); \
;     if ((++_sp & 255u) == 0u) { if (xb_ld(&(bar)[XB_TMO])) break; if (_sp > XB_SPIN_CAP) { atomicAdd(&(bar)[XB_TMO], 1u); break; } } } } while (0)
; __device__ __forceinline__ void xcd_barrier(const XcdBarrier& b) {
;     ...
;         const unsigned old = xb_add(&bar[XB_XSUB(b.x)], 1u);
;         const unsigned gen = old / nloc;
;         if (old + 1u == (gen + 1u) * nloc) {
;             __builtin_amdgcn_fence(__ATOMIC_RELEASE, "agent");
;             asm volatile("s_waitcnt vmcnt(0)" ::: "memory");
;             const unsigned og = xb_add(&bar[XB_TOP], 1u);
;             const unsigned tg = og / nx;
;             if (og + 1u == (tg + 1u) * nx) xb_add(&bar[XB_TOPGEN], 1u);
;             else XB_SPIN(xb_ld(&bar[XB_TOPGEN]) == tg, bar);
.LBB0_742:
	s_or_b64 exec, exec, s[12:13]
	v_cvt_f32_u32_e32 v4, v2
	s_waitcnt vmcnt(0)
	v_readfirstlane_b32 s1, v3
	v_sub_u32_e32 v3, 0, v2
	v_rcp_iflag_f32_e32 v4, v4
	v_add_u32_e32 v5, s1, v1
	v_mul_f32_e32 v4, 0x4f7ffffe, v4
	v_cvt_u32_f32_e32 v4, v4
	v_mul_lo_u32 v1, v3, v4
	v_mul_hi_u32 v1, v4, v1
	v_add_u32_e32 v1, v4, v1
	v_mul_hi_u32 v1, v5, v1
	v_mul_lo_u32 v3, v1, v2
	v_sub_u32_e32 v3, v5, v3
	v_add_u32_e32 v4, 1, v1
	v_cmp_ge_u32_e32 vcc, v3, v2
	s_nop 1
	v_cndmask_b32_e32 v1, v1, v4, vcc
	v_sub_u32_e32 v4, v3, v2
	v_cndmask_b32_e32 v3, v3, v4, vcc
	v_add_u32_e32 v4, 1, v1
	v_cmp_ge_u32_e32 vcc, v3, v2
	v_add_u32_e32 v3, 1, v5
	s_nop 0
	v_cndmask_b32_e32 v1, v1, v4, vcc
	v_mul_lo_u32 v4, v2, v1
	v_add_u32_e32 v2, v4, v2
	v_cmp_ne_u32_e32 vcc, v3, v2
	s_and_saveexec_b64 s[10:11], vcc
	s_xor_b64 s[10:11], exec, s[10:11]
	s_cbranch_execz .LBB0_756
	v_readlane_b32 s99, v255, 42
	s_cmp_ge_u32 s3, 18
	s_cselect_b32 s98, 18, 0
	s_sub_u32 s98, s3, s98
	s_cmp_eq_u32 s99, 0
	s_cbranch_scc1 .Lfull_f
	s_cmp_eq_u32 s98, 5
	s_cbranch_scc1 .Lnf_f
	s_cmp_eq_u32 s98, 6
	s_cbranch_scc1 .Lnf_f
	s_cmp_eq_u32 s98, 11
	s_cbranch_scc1 .Lnf_f

; __device__ __forceinline__ unsigned xb_ld(unsigned* p)              { return __hip_atomic_load(p, __ATOMIC_RELAXED, __HIP_MEMORY_SCOPE_AGENT); }
; #define XB_SPIN(cond, bar) do { unsigned _sp = 0; while (cond) { __builtin_amdgcn_s_sleep(0); \
;     if ((++_sp & 255u) == 0u) { if (xb_ld(&(bar)[XB_TMO])) break; if (_sp > XB_SPIN_CAP) { atomicAdd(&(bar)[XB_TMO], 1u); break; } } } } while (0)
; __device__ __forceinline__ void xcd_barrier(const XcdBarrier& b) {
;     ...
;         } else {
;             XB_SPIN(xb_ld(&bar[XB_XGEN(b.x)]) == gen, bar);
;             __builtin_amdgcn_fence(__ATOMIC_ACQUIRE, "agent");
;             asm volatile("s_waitcnt vmcnt(0)" ::: "memory");
.Lnf_f:
	s_waitcnt lgkmcnt(0)
	v_mov_b32_e32 v0, 0x2000
	global_load_dword v0, v0, s[8:9] offset:1024 sc1
	s_add_u32 s16, s8, 0x2400
	s_addc_u32 s17, s9, 0
	s_waitcnt vmcnt(0)
	v_cmp_eq_u32_e32 vcc, v0, v1
	s_and_saveexec_b64 s[12:13], vcc
	s_cbranch_execz .LBB0_755
	s_add_u32 s14, s30, 0x80200
	s_addc_u32 s15, s31, 0
	s_mov_b32 s1, 1
	s_mov_b64 s[18:19], 0
	s_branch .LBB0_746

; __device__ __forceinline__ unsigned xb_add(unsigned* p, unsigned v) { return __hip_atomic_fetch_add(p, v, __ATOMIC_RELAXED, __HIP_MEMORY_SCOPE_AGENT); }
; __device__ __forceinline__ void xcd_barrier(const XcdBarrier& b) {
;     ...
;         const unsigned old = xb_add(&bar[XB_XSUB(b.x)], 1u);
;         const unsigned gen = old / nloc;
;         if (old + 1u == (gen + 1u) * nloc) {
;             __builtin_amdgcn_fence(__ATOMIC_RELEASE, "agent");
;             asm volatile("s_waitcnt vmcnt(0)" ::: "memory");
;             const unsigned og = xb_add(&bar[XB_TOP], 1u);
;             const unsigned tg = og / nx;
;             if (og + 1u == (tg + 1u) * nx) xb_add(&bar[XB_TOPGEN], 1u);
.LBB0_756:
	s_andn2_saveexec_b64 s[10:11], s[10:11]
	s_cbranch_execz .LBB0_776
	s_mov_b64 s[10:11], exec
	v_readlane_b32 s99, v255, 42
	s_cmp_ge_u32 s3, 18
	s_cselect_b32 s98, 18, 0
	s_sub_u32 s98, s3, s98
	s_cmp_eq_u32 s99, 0
	s_cbranch_scc1 .Lfull_l
	s_cmp_eq_u32 s98, 5
	s_cbranch_scc1 .Lnf_l
	s_cmp_eq_u32 s98, 6
	s_cbranch_scc1 .Lnf_l
	s_cmp_eq_u32 s98, 11
	s_cbranch_scc1 .Lnf_l
.Lfull_l:
	buffer_wbl2 sc1
	buffer_inv sc1
.Lnf_l:
	s_waitcnt lgkmcnt(0)
	s_waitcnt vmcnt(0)
	v_mbcnt_lo_u32_b32 v1, s10, 0
	v_mbcnt_hi_u32_b32 v1, s11, v1
	v_cmp_eq_u32_e32 vcc, 0, v1
	s_and_saveexec_b64 s[12:13], vcc
	s_cbranch_execz .LBB0_759
	s_bcnt1_i32_b64 s1, s[10:11]
	v_mov_b32_e32 v2, s1
	v_mov_b32_e32 v3, 0x83000
	global_atomic_add v2, v3, v2, s[30:31] offset:1024 sc0
